# attention tasks handed out 8 consecutive query tiles per workgroup round (L1 sharing of K / V lines); HGRN gate coefficients of groups 1-3 computed by the partner wave
# speedup vs baseline: 1.0172x; 1.0172x over previous
.LBB0_819:
	s_cmp_lg_u32 s23, 0
	s_cbranch_scc1 .Lhg_skipcoef
	v_add_u32_e32 v48, 0, v46
	v_add_u32_e32 v50, 0, v45
	v_add_u32_e32 v49, 0x1c000, v48
	v_add_u32_e32 v51, 0x1a200, v50
	v_add_u32_e32 v52, 0x1c200, v50
	v_add_u32_e32 v50, 0, v44
	v_add_u32_e32 v48, 0x1a000, v48
	v_add_u32_e32 v53, 0x12000, v50
	v_add_u32_e32 v54, 0x12080, v50
	v_add_u32_e32 v55, 0x12100, v50
	v_add_u32_e32 v56, 0x12180, v50
	ds_read_u16 v49, v49
	ds_read_u16 v51, v51
	ds_read_u16 v52, v52
	ds_read_u16 v116, v53
	ds_read_u16 v117, v54
	ds_read_u16 v118, v55
	ds_read_u16 v119, v56
	ds_read_u16 v48, v48
	s_waitcnt lgkmcnt(7)
	v_lshlrev_b32_e32 v49, 16, v49
	v_mul_f32_e64 v53, |v49|, s83
	v_exp_f32_e32 v53, v53
	v_cmp_le_f32_e32 vcc, 0, v49
	s_waitcnt lgkmcnt(0)
	v_lshlrev_b32_e32 v48, 16, v48
	v_lshlrev_b32_e32 v52, 16, v52
	v_add_f32_e32 v54, 1.0, v53
	v_rcp_f32_e32 v54, v54
	v_mul_f32_e64 v55, |v52|, s83
	v_exp_f32_e32 v55, v55
	v_lshlrev_b32_e32 v51, 16, v51
	v_mul_f32_e32 v53, v53, v54
	v_cndmask_b32_e32 v49, v53, v54, vcc
	v_mul_f32_e32 v54, 0xbfb8aa3b, v48
	v_exp_f32_e32 v54, v54
	v_mul_f32_e32 v57, 0xbfb8aa3b, v51
	v_exp_f32_e32 v57, v57
	v_add_f32_e32 v56, 1.0, v55
	v_add_f32_e32 v54, 1.0, v54
	v_rcp_f32_e32 v54, v54
	v_fma_f32 v49, v31, v49, v23
	v_add_u32_e32 v53, v30, v33
	v_rcp_f32_e32 v56, v56
	v_mul_f32_e32 v48, v54, v48
	ds_write2_b32 v53, v49, v48 offset1:4
	v_add_f32_e32 v49, 1.0, v57
	v_rcp_f32_e32 v49, v49
	v_mul_f32_e32 v48, v55, v56
	v_cmp_le_f32_e32 vcc, 0, v52
	v_add_u32_e32 v52, 0x12380, v50
	v_mul_f32_e32 v49, v49, v51
	v_cndmask_b32_e32 v48, v48, v56, vcc
	v_fma_f32 v48, v31, v48, v23
	ds_write2_b32 v37, v48, v49 offset1:4
	s_branch .Lhg_go
.Lhg_skipcoef:
	v_add_u32_e32 v50, 0, v44
	v_add_u32_e32 v53, 0x12000, v50
	ds_read_u16 v116, v53
	ds_read_u16 v117, v53 offset:128
	ds_read_u16 v118, v53 offset:256
	ds_read_u16 v119, v53 offset:384
.Lhg_go:
	s_lshl_b32 s41, s40, 12
	s_add_i32 s41, s41, s18
	v_mov_b32_e32 v124, s41
	v_add_u32_e32 v125, 0x12000, v50
	v_lshl_add_u32 v51, s40, 15, v34
	ds_read_b128 v[52:55], v124 offset:0
	ds_read_b128 v[56:59], v124 offset:16
	ds_read_b128 v[60:63], v124 offset:32
	ds_read_b128 v[64:67], v124 offset:48
	ds_read_b128 v[68:71], v124 offset:64
	ds_read_b128 v[72:75], v124 offset:80
	ds_read_b128 v[76:79], v124 offset:96
	ds_read_b128 v[80:83], v124 offset:112
	s_waitcnt lgkmcnt(0)
	v_lshlrev_b32_e32 v126, 16, v116
	v_pk_add_f32 v[130:131], v[26:27], v[126:127] op_sel_hi:[1,0] neg_lo:[0,1] neg_hi:[0,1]
	v_pk_add_f32 v[132:133], v[24:25], v[126:127] op_sel_hi:[1,0] neg_lo:[0,1] neg_hi:[0,1]
	v_lshlrev_b32_e32 v128, 16, v117
	v_pk_fma_f32 v[26:27], v[130:131], v[52:53], v[126:127] op_sel_hi:[1,1,0]
	v_pk_fma_f32 v[24:25], v[132:133], v[54:55], v[126:127] op_sel_hi:[1,1,0]
	ds_read_u16 v120, v125 offset:512
	ds_read_u16 v121, v125 offset:640
	ds_read_u16 v122, v125 offset:768
	ds_read_u16 v123, v125 offset:896
	ds_read_b128 v[84:87], v124 offset:128
	ds_read_b128 v[88:91], v124 offset:144
	ds_read_b128 v[92:95], v124 offset:160
	ds_read_b128 v[96:99], v124 offset:176
	ds_read_b128 v[100:103], v124 offset:192
	ds_read_b128 v[104:107], v124 offset:208
	ds_read_b128 v[108:111], v124 offset:224
	ds_read_b128 v[112:115], v124 offset:240
	v_pk_mul_f32 v[134:135], v[58:59], v[24:25]
	v_pk_add_f32 v[130:131], v[26:27], v[128:129] op_sel_hi:[1,0] neg_lo:[0,1] neg_hi:[0,1]
	v_pk_add_f32 v[132:133], v[24:25], v[128:129] op_sel_hi:[1,0] neg_lo:[0,1] neg_hi:[0,1]
	v_lshlrev_b32_e32 v126, 16, v118
	v_pk_fma_f32 v[134:135], v[56:57], v[26:27], v[134:135]
	v_pk_fma_f32 v[26:27], v[130:131], v[60:61], v[128:129] op_sel_hi:[1,1,0]
	v_pk_fma_f32 v[24:25], v[132:133], v[62:63], v[128:129] op_sel_hi:[1,1,0]
	v_add_f32_e32 v136, v134, v135
	v_pk_mul_f32 v[134:135], v[66:67], v[24:25]
	v_pk_add_f32 v[130:131], v[26:27], v[126:127] op_sel_hi:[1,0] neg_lo:[0,1] neg_hi:[0,1]
	v_pk_add_f32 v[132:133], v[24:25], v[126:127] op_sel_hi:[1,0] neg_lo:[0,1] neg_hi:[0,1]
	v_lshlrev_b32_e32 v128, 16, v119
	v_pk_fma_f32 v[134:135], v[64:65], v[26:27], v[134:135]
	v_pk_fma_f32 v[26:27], v[130:131], v[68:69], v[126:127] op_sel_hi:[1,1,0]
	v_pk_fma_f32 v[24:25], v[132:133], v[70:71], v[126:127] op_sel_hi:[1,1,0]
	v_add_f32_e32 v137, v134, v135
	ds_write2st64_b32 v51, v136, v137 offset0:32 offset1:33
	v_pk_mul_f32 v[134:135], v[74:75], v[24:25]
	v_pk_add_f32 v[130:131], v[26:27], v[128:129] op_sel_hi:[1,0] neg_lo:[0,1] neg_hi:[0,1]
	v_pk_add_f32 v[132:133], v[24:25], v[128:129] op_sel_hi:[1,0] neg_lo:[0,1] neg_hi:[0,1]
	v_pk_fma_f32 v[134:135], v[72:73], v[26:27], v[134:135]
	v_pk_fma_f32 v[26:27], v[130:131], v[76:77], v[128:129] op_sel_hi:[1,1,0]
	v_pk_fma_f32 v[24:25], v[132:133], v[78:79], v[128:129] op_sel_hi:[1,1,0]
	v_add_f32_e32 v138, v134, v135
	s_waitcnt lgkmcnt(1)
	v_lshlrev_b32_e32 v126, 16, v120
	v_pk_mul_f32 v[134:135], v[82:83], v[24:25]
	v_pk_add_f32 v[130:131], v[26:27], v[126:127] op_sel_hi:[1,0] neg_lo:[0,1] neg_hi:[0,1]
	v_pk_add_f32 v[132:133], v[24:25], v[126:127] op_sel_hi:[1,0] neg_lo:[0,1] neg_hi:[0,1]
	v_lshlrev_b32_e32 v128, 16, v121
	v_pk_fma_f32 v[134:135], v[80:81], v[26:27], v[134:135]
	v_pk_fma_f32 v[26:27], v[130:131], v[84:85], v[126:127] op_sel_hi:[1,1,0]
	v_pk_fma_f32 v[24:25], v[132:133], v[86:87], v[126:127] op_sel_hi:[1,1,0]
	v_add_f32_e32 v139, v134, v135
	ds_write2st64_b32 v51, v138, v139 offset0:34 offset1:35
	ds_read_u16 v116, v125 offset:1024
	ds_read_u16 v117, v125 offset:1152
	ds_read_u16 v118, v125 offset:1280
	ds_read_u16 v119, v125 offset:1408
	ds_read_b128 v[52:55], v124 offset:256
	ds_read_b128 v[56:59], v124 offset:272
	ds_read_b128 v[60:63], v124 offset:288
	ds_read_b128 v[64:67], v124 offset:304
	ds_read_b128 v[68:71], v124 offset:320
	ds_read_b128 v[72:75], v124 offset:336
	ds_read_b128 v[76:79], v124 offset:352
	ds_read_b128 v[80:83], v124 offset:368
	v_pk_mul_f32 v[134:135], v[90:91], v[24:25]
	v_pk_add_f32 v[130:131], v[26:27], v[128:129] op_sel_hi:[1,0] neg_lo:[0,1] neg_hi:[0,1]
	v_pk_add_f32 v[132:133], v[24:25], v[128:129] op_sel_hi:[1,0] neg_lo:[0,1] neg_hi:[0,1]
	v_lshlrev_b32_e32 v126, 16, v122
	v_pk_fma_f32 v[134:135], v[88:89], v[26:27], v[134:135]
	v_pk_fma_f32 v[26:27], v[130:131], v[92:93], v[128:129] op_sel_hi:[1,1,0]
	v_pk_fma_f32 v[24:25], v[132:133], v[94:95], v[128:129] op_sel_hi:[1,1,0]
	v_add_f32_e32 v136, v134, v135
	v_pk_mul_f32 v[134:135], v[98:99], v[24:25]
	v_pk_add_f32 v[130:131], v[26:27], v[126:127] op_sel_hi:[1,0] neg_lo:[0,1] neg_hi:[0,1]
	v_pk_add_f32 v[132:133], v[24:25], v[126:127] op_sel_hi:[1,0] neg_lo:[0,1] neg_hi:[0,1]
	v_lshlrev_b32_e32 v128, 16, v123
	v_pk_fma_f32 v[134:135], v[96:97], v[26:27], v[134:135]
	v_pk_fma_f32 v[26:27], v[130:131], v[100:101], v[126:127] op_sel_hi:[1,1,0]
	v_pk_fma_f32 v[24:25], v[132:133], v[102:103], v[126:127] op_sel_hi:[1,1,0]
	v_add_f32_e32 v137, v134, v135
	ds_write2st64_b32 v51, v136, v137 offset0:36 offset1:37
	v_pk_mul_f32 v[134:135], v[106:107], v[24:25]
	v_pk_add_f32 v[130:131], v[26:27], v[128:129] op_sel_hi:[1,0] neg_lo:[0,1] neg_hi:[0,1]
	v_pk_add_f32 v[132:133], v[24:25], v[128:129] op_sel_hi:[1,0] neg_lo:[0,1] neg_hi:[0,1]
	v_pk_fma_f32 v[134:135], v[104:105], v[26:27], v[134:135]
	v_pk_fma_f32 v[26:27], v[130:131], v[108:109], v[128:129] op_sel_hi:[1,1,0]
	v_pk_fma_f32 v[24:25], v[132:133], v[110:111], v[128:129] op_sel_hi:[1,1,0]
	v_add_f32_e32 v138, v134, v135
	s_waitcnt lgkmcnt(1)
	v_lshlrev_b32_e32 v126, 16, v116
	v_pk_mul_f32 v[134:135], v[114:115], v[24:25]
	v_pk_add_f32 v[130:131], v[26:27], v[126:127] op_sel_hi:[1,0] neg_lo:[0,1] neg_hi:[0,1]
	v_pk_add_f32 v[132:133], v[24:25], v[126:127] op_sel_hi:[1,0] neg_lo:[0,1] neg_hi:[0,1]
	v_lshlrev_b32_e32 v128, 16, v117
	v_pk_fma_f32 v[134:135], v[112:113], v[26:27], v[134:135]
	v_pk_fma_f32 v[26:27], v[130:131], v[52:53], v[126:127] op_sel_hi:[1,1,0]
	v_pk_fma_f32 v[24:25], v[132:133], v[54:55], v[126:127] op_sel_hi:[1,1,0]
	v_add_f32_e32 v139, v134, v135
	ds_write2st64_b32 v51, v138, v139 offset0:38 offset1:39
	ds_read_u16 v120, v125 offset:1536
	ds_read_u16 v121, v125 offset:1664
	ds_read_u16 v122, v125 offset:1792
	ds_read_u16 v123, v125 offset:1920
	ds_read_b128 v[84:87], v124 offset:384
	ds_read_b128 v[88:91], v124 offset:400
	ds_read_b128 v[92:95], v124 offset:416
	ds_read_b128 v[96:99], v124 offset:432
	ds_read_b128 v[100:103], v124 offset:448
	ds_read_b128 v[104:107], v124 offset:464
	ds_read_b128 v[108:111], v124 offset:480
	ds_read_b128 v[112:115], v124 offset:496
	v_pk_mul_f32 v[134:135], v[58:59], v[24:25]
	v_pk_add_f32 v[130:131], v[26:27], v[128:129] op_sel_hi:[1,0] neg_lo:[0,1] neg_hi:[0,1]
	v_pk_add_f32 v[132:133], v[24:25], v[128:129] op_sel_hi:[1,0] neg_lo:[0,1] neg_hi:[0,1]
	v_lshlrev_b32_e32 v126, 16, v118
	v_pk_fma_f32 v[134:135], v[56:57], v[26:27], v[134:135]
	v_pk_fma_f32 v[26:27], v[130:131], v[60:61], v[128:129] op_sel_hi:[1,1,0]
	v_pk_fma_f32 v[24:25], v[132:133], v[62:63], v[128:129] op_sel_hi:[1,1,0]
	v_add_f32_e32 v136, v134, v135
	v_pk_mul_f32 v[134:135], v[66:67], v[24:25]
	v_pk_add_f32 v[130:131], v[26:27], v[126:127] op_sel_hi:[1,0] neg_lo:[0,1] neg_hi:[0,1]
	v_pk_add_f32 v[132:133], v[24:25], v[126:127] op_sel_hi:[1,0] neg_lo:[0,1] neg_hi:[0,1]
	v_lshlrev_b32_e32 v128, 16, v119
	v_pk_fma_f32 v[134:135], v[64:65], v[26:27], v[134:135]
	v_pk_fma_f32 v[26:27], v[130:131], v[68:69], v[126:127] op_sel_hi:[1,1,0]
	v_pk_fma_f32 v[24:25], v[132:133], v[70:71], v[126:127] op_sel_hi:[1,1,0]
	v_add_f32_e32 v137, v134, v135
	ds_write2st64_b32 v51, v136, v137 offset0:40 offset1:41
	v_pk_mul_f32 v[134:135], v[74:75], v[24:25]
	v_pk_add_f32 v[130:131], v[26:27], v[128:129] op_sel_hi:[1,0] neg_lo:[0,1] neg_hi:[0,1]
	v_pk_add_f32 v[132:133], v[24:25], v[128:129] op_sel_hi:[1,0] neg_lo:[0,1] neg_hi:[0,1]
	v_pk_fma_f32 v[134:135], v[72:73], v[26:27], v[134:135]
	v_pk_fma_f32 v[26:27], v[130:131], v[76:77], v[128:129] op_sel_hi:[1,1,0]
	v_pk_fma_f32 v[24:25], v[132:133], v[78:79], v[128:129] op_sel_hi:[1,1,0]
	v_add_f32_e32 v138, v134, v135
	s_waitcnt lgkmcnt(1)
	v_lshlrev_b32_e32 v126, 16, v120
	v_pk_mul_f32 v[134:135], v[82:83], v[24:25]
	v_pk_add_f32 v[130:131], v[26:27], v[126:127] op_sel_hi:[1,0] neg_lo:[0,1] neg_hi:[0,1]
	v_pk_add_f32 v[132:133], v[24:25], v[126:127] op_sel_hi:[1,0] neg_lo:[0,1] neg_hi:[0,1]
	v_lshlrev_b32_e32 v128, 16, v121
	v_pk_fma_f32 v[134:135], v[80:81], v[26:27], v[134:135]
	v_pk_fma_f32 v[26:27], v[130:131], v[84:85], v[126:127] op_sel_hi:[1,1,0]
	v_pk_fma_f32 v[24:25], v[132:133], v[86:87], v[126:127] op_sel_hi:[1,1,0]
	v_add_f32_e32 v139, v134, v135
	ds_write2st64_b32 v51, v138, v139 offset0:42 offset1:43
	ds_read_u16 v116, v125 offset:2048
	ds_read_u16 v117, v125 offset:2176
	ds_read_u16 v118, v125 offset:2304
	ds_read_u16 v119, v125 offset:2432
	ds_read_b128 v[52:55], v124 offset:512
	ds_read_b128 v[56:59], v124 offset:528
	ds_read_b128 v[60:63], v124 offset:544
	ds_read_b128 v[64:67], v124 offset:560
	ds_read_b128 v[68:71], v124 offset:576
	ds_read_b128 v[72:75], v124 offset:592
	ds_read_b128 v[76:79], v124 offset:608
	ds_read_b128 v[80:83], v124 offset:624
	v_pk_mul_f32 v[134:135], v[90:91], v[24:25]
	v_pk_add_f32 v[130:131], v[26:27], v[128:129] op_sel_hi:[1,0] neg_lo:[0,1] neg_hi:[0,1]
	v_pk_add_f32 v[132:133], v[24:25], v[128:129] op_sel_hi:[1,0] neg_lo:[0,1] neg_hi:[0,1]
	v_lshlrev_b32_e32 v126, 16, v122
	v_pk_fma_f32 v[134:135], v[88:89], v[26:27], v[134:135]
	v_pk_fma_f32 v[26:27], v[130:131], v[92:93], v[128:129] op_sel_hi:[1,1,0]
	v_pk_fma_f32 v[24:25], v[132:133], v[94:95], v[128:129] op_sel_hi:[1,1,0]
	v_add_f32_e32 v136, v134, v135
	v_pk_mul_f32 v[134:135], v[98:99], v[24:25]
	v_pk_add_f32 v[130:131], v[26:27], v[126:127] op_sel_hi:[1,0] neg_lo:[0,1] neg_hi:[0,1]
	v_pk_add_f32 v[132:133], v[24:25], v[126:127] op_sel_hi:[1,0] neg_lo:[0,1] neg_hi:[0,1]
	v_lshlrev_b32_e32 v128, 16, v123
	v_pk_fma_f32 v[134:135], v[96:97], v[26:27], v[134:135]
	v_pk_fma_f32 v[26:27], v[130:131], v[100:101], v[126:127] op_sel_hi:[1,1,0]
	v_pk_fma_f32 v[24:25], v[132:133], v[102:103], v[126:127] op_sel_hi:[1,1,0]
	v_add_f32_e32 v137, v134, v135
	ds_write2st64_b32 v51, v136, v137 offset0:44 offset1:45
	v_pk_mul_f32 v[134:135], v[106:107], v[24:25]
	v_pk_add_f32 v[130:131], v[26:27], v[128:129] op_sel_hi:[1,0] neg_lo:[0,1] neg_hi:[0,1]
	v_pk_add_f32 v[132:133], v[24:25], v[128:129] op_sel_hi:[1,0] neg_lo:[0,1] neg_hi:[0,1]
	v_pk_fma_f32 v[134:135], v[104:105], v[26:27], v[134:135]
	v_pk_fma_f32 v[26:27], v[130:131], v[108:109], v[128:129] op_sel_hi:[1,1,0]
	v_pk_fma_f32 v[24:25], v[132:133], v[110:111], v[128:129] op_sel_hi:[1,1,0]
	v_add_f32_e32 v138, v134, v135
	s_waitcnt lgkmcnt(1)
	v_lshlrev_b32_e32 v126, 16, v116
	v_pk_mul_f32 v[134:135], v[114:115], v[24:25]
	v_pk_add_f32 v[130:131], v[26:27], v[126:127] op_sel_hi:[1,0] neg_lo:[0,1] neg_hi:[0,1]
	v_pk_add_f32 v[132:133], v[24:25], v[126:127] op_sel_hi:[1,0] neg_lo:[0,1] neg_hi:[0,1]
	v_lshlrev_b32_e32 v128, 16, v117
	v_pk_fma_f32 v[134:135], v[112:113], v[26:27], v[134:135]
	v_pk_fma_f32 v[26:27], v[130:131], v[52:53], v[126:127] op_sel_hi:[1,1,0]
	v_pk_fma_f32 v[24:25], v[132:133], v[54:55], v[126:127] op_sel_hi:[1,1,0]
	v_add_f32_e32 v139, v134, v135
	ds_write2st64_b32 v51, v138, v139 offset0:46 offset1:47
	ds_read_u16 v120, v125 offset:2560
	ds_read_u16 v121, v125 offset:2688
	ds_read_u16 v122, v125 offset:2816
	ds_read_u16 v123, v125 offset:2944
	ds_read_b128 v[84:87], v124 offset:640
	ds_read_b128 v[88:91], v124 offset:656
	ds_read_b128 v[92:95], v124 offset:672
	ds_read_b128 v[96:99], v124 offset:688
	ds_read_b128 v[100:103], v124 offset:704
	ds_read_b128 v[104:107], v124 offset:720
	ds_read_b128 v[108:111], v124 offset:736
	ds_read_b128 v[112:115], v124 offset:752
	v_pk_mul_f32 v[134:135], v[58:59], v[24:25]
	v_pk_add_f32 v[130:131], v[26:27], v[128:129] op_sel_hi:[1,0] neg_lo:[0,1] neg_hi:[0,1]
	v_pk_add_f32 v[132:133], v[24:25], v[128:129] op_sel_hi:[1,0] neg_lo:[0,1] neg_hi:[0,1]
	v_lshlrev_b32_e32 v126, 16, v118
	v_pk_fma_f32 v[134:135], v[56:57], v[26:27], v[134:135]
	v_pk_fma_f32 v[26:27], v[130:131], v[60:61], v[128:129] op_sel_hi:[1,1,0]
	v_pk_fma_f32 v[24:25], v[132:133], v[62:63], v[128:129] op_sel_hi:[1,1,0]
	v_add_f32_e32 v136, v134, v135
	v_pk_mul_f32 v[134:135], v[66:67], v[24:25]
	v_pk_add_f32 v[130:131], v[26:27], v[126:127] op_sel_hi:[1,0] neg_lo:[0,1] neg_hi:[0,1]
	v_pk_add_f32 v[132:133], v[24:25], v[126:127] op_sel_hi:[1,0] neg_lo:[0,1] neg_hi:[0,1]
	v_lshlrev_b32_e32 v128, 16, v119
	v_pk_fma_f32 v[134:135], v[64:65], v[26:27], v[134:135]
	v_pk_fma_f32 v[26:27], v[130:131], v[68:69], v[126:127] op_sel_hi:[1,1,0]
	v_pk_fma_f32 v[24:25], v[132:133], v[70:71], v[126:127] op_sel_hi:[1,1,0]
	v_add_f32_e32 v137, v134, v135
	ds_write2st64_b32 v51, v136, v137 offset0:48 offset1:49
	v_pk_mul_f32 v[134:135], v[74:75], v[24:25]
	v_pk_add_f32 v[130:131], v[26:27], v[128:129] op_sel_hi:[1,0] neg_lo:[0,1] neg_hi:[0,1]
	v_pk_add_f32 v[132:133], v[24:25], v[128:129] op_sel_hi:[1,0] neg_lo:[0,1] neg_hi:[0,1]
	v_pk_fma_f32 v[134:135], v[72:73], v[26:27], v[134:135]
	v_pk_fma_f32 v[26:27], v[130:131], v[76:77], v[128:129] op_sel_hi:[1,1,0]
	v_pk_fma_f32 v[24:25], v[132:133], v[78:79], v[128:129] op_sel_hi:[1,1,0]
	v_add_f32_e32 v138, v134, v135
	s_waitcnt lgkmcnt(1)
	v_lshlrev_b32_e32 v126, 16, v120
	v_pk_mul_f32 v[134:135], v[82:83], v[24:25]
	v_pk_add_f32 v[130:131], v[26:27], v[126:127] op_sel_hi:[1,0] neg_lo:[0,1] neg_hi:[0,1]
	v_pk_add_f32 v[132:133], v[24:25], v[126:127] op_sel_hi:[1,0] neg_lo:[0,1] neg_hi:[0,1]
	v_lshlrev_b32_e32 v128, 16, v121
	v_pk_fma_f32 v[134:135], v[80:81], v[26:27], v[134:135]
	v_pk_fma_f32 v[26:27], v[130:131], v[84:85], v[126:127] op_sel_hi:[1,1,0]
	v_pk_fma_f32 v[24:25], v[132:133], v[86:87], v[126:127] op_sel_hi:[1,1,0]
	v_add_f32_e32 v139, v134, v135
	ds_write2st64_b32 v51, v138, v139 offset0:50 offset1:51
	ds_read_u16 v116, v125 offset:3072
	ds_read_u16 v117, v125 offset:3200
	ds_read_u16 v118, v125 offset:3328
	ds_read_u16 v119, v125 offset:3456
	ds_read_b128 v[52:55], v124 offset:768
	ds_read_b128 v[56:59], v124 offset:784
	ds_read_b128 v[60:63], v124 offset:800
	ds_read_b128 v[64:67], v124 offset:816
	ds_read_b128 v[68:71], v124 offset:832
	ds_read_b128 v[72:75], v124 offset:848
	ds_read_b128 v[76:79], v124 offset:864
	ds_read_b128 v[80:83], v124 offset:880
	v_pk_mul_f32 v[134:135], v[90:91], v[24:25]
	v_pk_add_f32 v[130:131], v[26:27], v[128:129] op_sel_hi:[1,0] neg_lo:[0,1] neg_hi:[0,1]
	v_pk_add_f32 v[132:133], v[24:25], v[128:129] op_sel_hi:[1,0] neg_lo:[0,1] neg_hi:[0,1]
	v_lshlrev_b32_e32 v126, 16, v122
	v_pk_fma_f32 v[134:135], v[88:89], v[26:27], v[134:135]
	v_pk_fma_f32 v[26:27], v[130:131], v[92:93], v[128:129] op_sel_hi:[1,1,0]
	v_pk_fma_f32 v[24:25], v[132:133], v[94:95], v[128:129] op_sel_hi:[1,1,0]
	v_add_f32_e32 v136, v134, v135
	v_pk_mul_f32 v[134:135], v[98:99], v[24:25]
	v_pk_add_f32 v[130:131], v[26:27], v[126:127] op_sel_hi:[1,0] neg_lo:[0,1] neg_hi:[0,1]
	v_pk_add_f32 v[132:133], v[24:25], v[126:127] op_sel_hi:[1,0] neg_lo:[0,1] neg_hi:[0,1]
	v_lshlrev_b32_e32 v128, 16, v123
	v_pk_fma_f32 v[134:135], v[96:97], v[26:27], v[134:135]
	v_pk_fma_f32 v[26:27], v[130:131], v[100:101], v[126:127] op_sel_hi:[1,1,0]
	v_pk_fma_f32 v[24:25], v[132:133], v[102:103], v[126:127] op_sel_hi:[1,1,0]
	v_add_f32_e32 v137, v134, v135
	ds_write2st64_b32 v51, v136, v137 offset0:52 offset1:53
	v_pk_mul_f32 v[134:135], v[106:107], v[24:25]
	v_pk_add_f32 v[130:131], v[26:27], v[128:129] op_sel_hi:[1,0] neg_lo:[0,1] neg_hi:[0,1]
	v_pk_add_f32 v[132:133], v[24:25], v[128:129] op_sel_hi:[1,0] neg_lo:[0,1] neg_hi:[0,1]
	v_pk_fma_f32 v[134:135], v[104:105], v[26:27], v[134:135]
	v_pk_fma_f32 v[26:27], v[130:131], v[108:109], v[128:129] op_sel_hi:[1,1,0]
	v_pk_fma_f32 v[24:25], v[132:133], v[110:111], v[128:129] op_sel_hi:[1,1,0]
	v_add_f32_e32 v138, v134, v135
	s_waitcnt lgkmcnt(1)
	v_lshlrev_b32_e32 v126, 16, v116
	v_pk_mul_f32 v[134:135], v[114:115], v[24:25]
	v_pk_add_f32 v[130:131], v[26:27], v[126:127] op_sel_hi:[1,0] neg_lo:[0,1] neg_hi:[0,1]
	v_pk_add_f32 v[132:133], v[24:25], v[126:127] op_sel_hi:[1,0] neg_lo:[0,1] neg_hi:[0,1]
	v_lshlrev_b32_e32 v128, 16, v117
	v_pk_fma_f32 v[134:135], v[112:113], v[26:27], v[134:135]
	v_pk_fma_f32 v[26:27], v[130:131], v[52:53], v[126:127] op_sel_hi:[1,1,0]
	v_pk_fma_f32 v[24:25], v[132:133], v[54:55], v[126:127] op_sel_hi:[1,1,0]
	v_add_f32_e32 v139, v134, v135
	ds_write2st64_b32 v51, v138, v139 offset0:54 offset1:55
	ds_read_u16 v120, v125 offset:3584
	ds_read_u16 v121, v125 offset:3712
	ds_read_u16 v122, v125 offset:3840
	ds_read_u16 v123, v125 offset:3968
	ds_read_b128 v[84:87], v124 offset:896
	ds_read_b128 v[88:91], v124 offset:912
	ds_read_b128 v[92:95], v124 offset:928
	ds_read_b128 v[96:99], v124 offset:944
	ds_read_b128 v[100:103], v124 offset:960
	ds_read_b128 v[104:107], v124 offset:976
	ds_read_b128 v[108:111], v124 offset:992
	ds_read_b128 v[112:115], v124 offset:1008
	v_pk_mul_f32 v[134:135], v[58:59], v[24:25]
	v_pk_add_f32 v[130:131], v[26:27], v[128:129] op_sel_hi:[1,0] neg_lo:[0,1] neg_hi:[0,1]
	v_pk_add_f32 v[132:133], v[24:25], v[128:129] op_sel_hi:[1,0] neg_lo:[0,1] neg_hi:[0,1]
	v_lshlrev_b32_e32 v126, 16, v118
	v_pk_fma_f32 v[134:135], v[56:57], v[26:27], v[134:135]
	v_pk_fma_f32 v[26:27], v[130:131], v[60:61], v[128:129] op_sel_hi:[1,1,0]
	v_pk_fma_f32 v[24:25], v[132:133], v[62:63], v[128:129] op_sel_hi:[1,1,0]
	v_add_f32_e32 v136, v134, v135
	v_pk_mul_f32 v[134:135], v[66:67], v[24:25]
	v_pk_add_f32 v[130:131], v[26:27], v[126:127] op_sel_hi:[1,0] neg_lo:[0,1] neg_hi:[0,1]
	v_pk_add_f32 v[132:133], v[24:25], v[126:127] op_sel_hi:[1,0] neg_lo:[0,1] neg_hi:[0,1]
	v_lshlrev_b32_e32 v128, 16, v119
	v_pk_fma_f32 v[134:135], v[64:65], v[26:27], v[134:135]
	v_pk_fma_f32 v[26:27], v[130:131], v[68:69], v[126:127] op_sel_hi:[1,1,0]
	v_pk_fma_f32 v[24:25], v[132:133], v[70:71], v[126:127] op_sel_hi:[1,1,0]
	v_add_f32_e32 v137, v134, v135
	ds_write2st64_b32 v51, v136, v137 offset0:56 offset1:57
	v_pk_mul_f32 v[134:135], v[74:75], v[24:25]
	v_pk_add_f32 v[130:131], v[26:27], v[128:129] op_sel_hi:[1,0] neg_lo:[0,1] neg_hi:[0,1]
	v_pk_add_f32 v[132:133], v[24:25], v[128:129] op_sel_hi:[1,0] neg_lo:[0,1] neg_hi:[0,1]
	v_pk_fma_f32 v[134:135], v[72:73], v[26:27], v[134:135]
	v_pk_fma_f32 v[26:27], v[130:131], v[76:77], v[128:129] op_sel_hi:[1,1,0]
	v_pk_fma_f32 v[24:25], v[132:133], v[78:79], v[128:129] op_sel_hi:[1,1,0]
	v_add_f32_e32 v138, v134, v135
	s_waitcnt lgkmcnt(1)
	v_lshlrev_b32_e32 v126, 16, v120
	v_pk_mul_f32 v[134:135], v[82:83], v[24:25]
	v_pk_add_f32 v[130:131], v[26:27], v[126:127] op_sel_hi:[1,0] neg_lo:[0,1] neg_hi:[0,1]
	v_pk_add_f32 v[132:133], v[24:25], v[126:127] op_sel_hi:[1,0] neg_lo:[0,1] neg_hi:[0,1]
	v_lshlrev_b32_e32 v128, 16, v121
	v_pk_fma_f32 v[134:135], v[80:81], v[26:27], v[134:135]
	v_pk_fma_f32 v[26:27], v[130:131], v[84:85], v[126:127] op_sel_hi:[1,1,0]
	v_pk_fma_f32 v[24:25], v[132:133], v[86:87], v[126:127] op_sel_hi:[1,1,0]
	v_add_f32_e32 v139, v134, v135
	ds_write2st64_b32 v51, v138, v139 offset0:58 offset1:59
	v_pk_mul_f32 v[134:135], v[90:91], v[24:25]
	v_pk_add_f32 v[130:131], v[26:27], v[128:129] op_sel_hi:[1,0] neg_lo:[0,1] neg_hi:[0,1]
	v_pk_add_f32 v[132:133], v[24:25], v[128:129] op_sel_hi:[1,0] neg_lo:[0,1] neg_hi:[0,1]
	v_lshlrev_b32_e32 v126, 16, v122
	v_pk_fma_f32 v[134:135], v[88:89], v[26:27], v[134:135]
	v_pk_fma_f32 v[26:27], v[130:131], v[92:93], v[128:129] op_sel_hi:[1,1,0]
	v_pk_fma_f32 v[24:25], v[132:133], v[94:95], v[128:129] op_sel_hi:[1,1,0]
	v_add_f32_e32 v136, v134, v135
	v_pk_mul_f32 v[134:135], v[98:99], v[24:25]
	v_pk_add_f32 v[130:131], v[26:27], v[126:127] op_sel_hi:[1,0] neg_lo:[0,1] neg_hi:[0,1]
	v_pk_add_f32 v[132:133], v[24:25], v[126:127] op_sel_hi:[1,0] neg_lo:[0,1] neg_hi:[0,1]
	v_lshlrev_b32_e32 v128, 16, v123
	v_pk_fma_f32 v[134:135], v[96:97], v[26:27], v[134:135]
	v_pk_fma_f32 v[26:27], v[130:131], v[100:101], v[126:127] op_sel_hi:[1,1,0]
	v_pk_fma_f32 v[24:25], v[132:133], v[102:103], v[126:127] op_sel_hi:[1,1,0]
	v_add_f32_e32 v137, v134, v135
	ds_write2st64_b32 v51, v136, v137 offset0:60 offset1:61
	v_pk_mul_f32 v[134:135], v[106:107], v[24:25]
	v_pk_add_f32 v[130:131], v[26:27], v[128:129] op_sel_hi:[1,0] neg_lo:[0,1] neg_hi:[0,1]
	v_pk_add_f32 v[132:133], v[24:25], v[128:129] op_sel_hi:[1,0] neg_lo:[0,1] neg_hi:[0,1]
	v_pk_fma_f32 v[134:135], v[104:105], v[26:27], v[134:135]
	v_pk_fma_f32 v[26:27], v[130:131], v[108:109], v[128:129] op_sel_hi:[1,1,0]
	v_pk_fma_f32 v[24:25], v[132:133], v[110:111], v[128:129] op_sel_hi:[1,1,0]
	v_add_f32_e32 v138, v134, v135
	v_pk_mul_f32 v[134:135], v[114:115], v[24:25]
	s_nop 0
	v_pk_fma_f32 v[134:135], v[112:113], v[26:27], v[134:135]
	s_nop 0
	v_add_f32_e32 v139, v134, v135
	ds_write2st64_b32 v51, v138, v139 offset0:62 offset1:63
	s_branch .LBB0_820
.Lhg_helper:
	s_cmp_eq_u32 s23, 3
	s_cbranch_scc1 .LBB0_820
	v_add_u32_e32 v48, 0x3e0, v46
	v_add_u32_e32 v50, 0x3e0, v45
	v_add_u32_e32 v49, 0x1c000, v48
	v_add_u32_e32 v51, 0x1a200, v50
	v_add_u32_e32 v52, 0x1c200, v50
	v_add_u32_e32 v48, 0x1a000, v48
	ds_read_u16 v49, v49
	ds_read_u16 v51, v51
	ds_read_u16 v52, v52
	ds_read_u16 v48, v48
	s_xor_b32 s41, s40, 1
	s_lshl_b32 s41, s41, 12
	s_waitcnt lgkmcnt(3)
	v_lshlrev_b32_e32 v49, 16, v49
	v_mul_f32_e64 v53, |v49|, s83
	v_exp_f32_e32 v53, v53
	v_cmp_le_f32_e32 vcc, 0, v49
	s_waitcnt lgkmcnt(0)
	v_lshlrev_b32_e32 v48, 16, v48
	v_lshlrev_b32_e32 v52, 16, v52
	v_add_f32_e32 v54, 1.0, v53
	v_rcp_f32_e32 v54, v54
	v_mul_f32_e64 v55, |v52|, s83
	v_exp_f32_e32 v55, v55
	v_lshlrev_b32_e32 v51, 16, v51
	v_mul_f32_e32 v53, v53, v54
	v_cndmask_b32_e32 v49, v53, v54, vcc
	v_mul_f32_e32 v54, 0xbfb8aa3b, v48
	v_exp_f32_e32 v54, v54
	v_mul_f32_e32 v57, 0xbfb8aa3b, v51
	v_exp_f32_e32 v57, v57
	v_add_f32_e32 v56, 1.0, v55
	v_add_f32_e32 v54, 1.0, v54
	v_rcp_f32_e32 v54, v54
	v_fma_f32 v49, v31, v49, v23
	v_add3_u32 v53, v30, v33, s41
	v_rcp_f32_e32 v56, v56
	v_mul_f32_e32 v48, v54, v48
	ds_write2_b32 v53, v49, v48 offset1:4
	v_add_f32_e32 v49, 1.0, v57
	v_rcp_f32_e32 v49, v49
	v_mul_f32_e32 v48, v55, v56
	v_cmp_le_f32_e32 vcc, 0, v52
	v_add_u32_e32 v52, s41, v37
	v_mul_f32_e32 v49, v49, v51
	v_cndmask_b32_e32 v48, v48, v56, vcc
	v_fma_f32 v48, v31, v48, v23
	ds_write2_b32 v52, v48, v49 offset1:4

.LBB0_836:
	v_readlane_b32 s35, v253, 32
	s_lshl_b32 s44, s35, 6
	s_waitcnt vmcnt(0)
	v_mov_b32_e32 v2, v179
	s_lshl_b64 s[22:23], s[44:45], 2
	v_readlane_b32 s0, v251, 38
	s_add_u32 s40, s0, s22
	v_readlane_b32 s0, v251, 39
	v_bfe_u32 v1, v2, 4, 2
	v_readlane_b32 s10, v250, 59
	v_readlane_b32 s48, v249, 8
	v_and_b32_e32 v0, 63, v2
	s_addc_u32 s41, s0, s23
	v_and_b32_e32 v32, 15, v2
	v_lshlrev_b32_e32 v34, 3, v1
	v_mov_b32_e32 v35, v157
	v_readlane_b32 s11, v250, 60
	v_readlane_b32 s52, v249, 12
	v_cmp_eq_u32_e64 s[0:1], 0, v0
	v_lshlrev_b32_e32 v36, 2, v1
	v_cmp_eq_u32_e64 s[4:5], 3, v1
	v_cmp_gt_u32_e64 s[6:7], 32, v0
	v_cmp_gt_u32_e64 s[8:9], 16, v0
	v_lshlrev_b32_e32 v156, 6, v32
	v_lshl_add_u64 v[0:1], s[10:11], 0, v[34:35]
	v_readlane_b32 s49, v249, 9
	v_readlane_b32 s50, v249, 10
	v_readlane_b32 s51, v249, 11
	v_readlane_b32 s53, v249, 13
	v_readlane_b32 s56, v249, 16
	v_readlane_b32 s57, v249, 17
	v_readlane_b32 s60, v249, 20
	v_readlane_b32 s61, v249, 21
	s_add_u32 s10, s52, s22
	v_lshl_add_u64 v[38:39], v[0:1], 0, v[156:157]
	v_readlane_b32 s54, v249, 14
	v_readlane_b32 s55, v249, 15
	v_readlane_b32 s62, v249, 22
	s_addc_u32 s11, s53, s23
	v_and_b32_e32 v156, 48, v2
	v_readlane_b32 s60, v253, 17
	v_readlane_b32 s88, v253, 19
	v_readlane_b32 s50, v253, 21
	v_readlane_b32 s48, v253, 23
	v_readlane_b32 s52, v253, 25
	v_readlane_b32 s56, v249, 51
	v_readlane_b32 s70, v253, 37
	v_readlane_b32 s74, v253, 35
	v_readlane_b32 s94, v253, 33
	v_lshl_add_u64 v[40:41], s[10:11], 0, v[156:157]
	v_readlane_b32 s61, v253, 18
	v_readlane_b32 s89, v253, 20
	v_readlane_b32 s51, v253, 22
	v_readlane_b32 s49, v253, 24
	v_readlane_b32 s53, v253, 26
	v_readlane_b32 s57, v249, 52
	v_readlane_b32 s62, v253, 27
	s_mov_b64 s[54:55], 0x1200
	v_readlane_b32 s71, v253, 38
	v_readlane_b32 s75, v253, 36
	v_readlane_b32 s95, v253, 34
	v_readlane_b32 s58, v249, 18
	v_readlane_b32 s59, v249, 19
	v_readlane_b32 s63, v249, 23
	v_readfirstlane_b32 s100, v179
	v_mov_b32_e32 v82, 0x23ff8
	s_lshr_b32 s100, s100, 6
	s_cmp_lg_u32 s100, 0
	s_cbranch_scc1 .Lsbg_e1
	s_mov_b64 s[10:11], exec
	s_mov_b64 exec, s[0:1]
	v_mov_b32_e32 v81, 8
	global_atomic_add v81, v157, v81, s[40:41] sc0
	s_mov_b64 exec, s[10:11]
.Lsbg_e1:
	s_branch .LBB0_838

.LBB0_838:
	s_waitcnt lgkmcnt(0)
	s_barrier
	s_cmp_lg_u32 s100, 0
	s_cbranch_scc1 .Lsbg_w
	s_waitcnt vmcnt(0)
	s_mov_b64 s[14:15], exec
	s_mov_b64 exec, s[0:1]
	ds_write_b32 v82, v81
	s_nop 0
	v_mov_b32_e32 v81, 8
	global_atomic_add v81, v157, v81, s[40:41] sc0
	s_mov_b64 exec, s[14:15]
	s_waitcnt lgkmcnt(0)
.Lsbg_w:
	s_barrier
	ds_read_b32 v83, v82
	s_waitcnt lgkmcnt(0)
	v_readfirstlane_b32 s12, v83
	s_cmpk_gt_i32 s12, 0xfff
	s_mov_b64 s[10:11], -1
	s_cbranch_scc1 .LBB0_837
	s_add_i32 s12, s12, s100
	s_ashr_i32 s14, s12, 9
	s_lshl_b32 s16, s12, 4
	s_and_b32 s11, s16, 0x7f0
	s_ashr_i32 s15, s14, 31
	s_ashr_i32 s10, s12, 7
	s_lshl_b64 s[12:13], s[14:15], 11
	v_or_b32_e32 v33, s11, v32
	v_or_b32_e32 v42, s12, v33
	v_mov_b64_e32 v[0:1], s[20:21]
	s_lshl_b32 s11, s10, 6
	v_mad_u64_u32 v[0:1], s[14:15], v42, s90, v[0:1]
	s_and_b32 s46, s11, 0xc0
	v_mad_i32_i24 v1, s13, v222, v1
	s_lshl_b32 s44, s46, 1
	v_lshl_add_u64 v[0:1], v[0:1], 0, s[44:45]
	v_lshlrev_b32_e32 v156, 1, v34
	v_lshl_add_u64 v[0:1], v[0:1], 0, v[156:157]
	global_load_dwordx4 v[16:19], v[0:1], off
	global_load_dwordx4 v[20:23], v[0:1], off offset:64
	v_and_b32_e32 v0, 63, v217
	v_cmp_gt_u32_e32 vcc, 48, v0
	s_ashr_i32 s11, s10, 31
	s_lshl_b64 s[10:11], s[10:11], 18
	v_cndmask_b32_e64 v1, 0, 16, vcc
	v_cmp_gt_u32_e32 vcc, 16, v0
	v_mov_b32_e32 v28, 0
	v_mov_b32_e32 v43, s13
	v_cndmask_b32_e64 v0, 0, 48, vcc
	v_add_lshl_u32 v50, v0, v217, 2
	v_and_or_b32 v0, v217, 64, v32
	v_mov_b32_e32 v45, s13
	v_or_b32_e32 v44, s12, v32
	v_add_lshl_u32 v35, v1, v217, 2
	v_lshl_or_b32 v37, v217, 2, v223
	v_lshlrev_b32_e32 v51, 2, v0
	v_lshl_add_u64 v[46:47], v[38:39], 0, s[10:11]
	s_and_b32 s58, s16, 0x7e0
	v_mov_b32_e32 v0, 0
	v_mov_b32_e32 v1, v28
	v_mov_b32_e32 v2, v28
	v_mov_b32_e32 v3, v28
	v_mov_b32_e32 v4, 0
	v_mov_b32_e32 v5, v28
	v_mov_b32_e32 v6, v28
	v_mov_b32_e32 v7, v28
	v_mov_b32_e32 v8, 0
	v_mov_b32_e32 v9, v28
	v_mov_b32_e32 v10, v28
	v_mov_b32_e32 v11, v28
	v_mov_b32_e32 v12, 0
	v_mov_b32_e32 v13, v28
	v_mov_b32_e32 v14, v28
	v_mov_b32_e32 v15, v28

	.amdhsa_kernel _Z14fwd_megakernel6Params
		.amdhsa_group_segment_fixed_size 0
		.amdhsa_private_segment_fixed_size 0
		.amdhsa_kernarg_size 440
		.amdhsa_user_sgpr_count 2
		.amdhsa_user_sgpr_dispatch_ptr 0
		.amdhsa_user_sgpr_queue_ptr 0
		.amdhsa_user_sgpr_kernarg_segment_ptr 1
		.amdhsa_user_sgpr_dispatch_id 0
		.amdhsa_user_sgpr_kernarg_preload_length 0
		.amdhsa_user_sgpr_kernarg_preload_offset 0
		.amdhsa_user_sgpr_private_segment_size 0
		.amdhsa_uses_dynamic_stack 0
		.amdhsa_enable_private_segment 0
		.amdhsa_system_sgpr_workgroup_id_x 1
		.amdhsa_system_sgpr_workgroup_id_y 0
		.amdhsa_system_sgpr_workgroup_id_z 0
		.amdhsa_system_sgpr_workgroup_info 0
		.amdhsa_system_vgpr_workitem_id 2
		.amdhsa_next_free_vgpr 256
		.amdhsa_next_free_sgpr 102
		.amdhsa_accum_offset 256
		.amdhsa_reserve_vcc 1
		.amdhsa_float_round_mode_32 0
		.amdhsa_float_round_mode_16_64 0
		.amdhsa_float_denorm_mode_32 3
		.amdhsa_float_denorm_mode_16_64 3
		.amdhsa_dx10_clamp 1
		.amdhsa_ieee_mode 1
		.amdhsa_fp16_overflow 0
		.amdhsa_tg_split 0
		.amdhsa_exception_fp_ieee_invalid_op 0
		.amdhsa_exception_fp_denorm_src 0
		.amdhsa_exception_fp_ieee_div_zero 0
		.amdhsa_exception_fp_ieee_overflow 0
		.amdhsa_exception_fp_ieee_underflow 0
		.amdhsa_exception_fp_ieee_inexact 0
		.amdhsa_exception_int_div_zero 0
	.end_amdhsa_kernel

amdhsa.kernels:
  - .agpr_count:     0
    .args:
      - .offset:         0
        .size:           184
        .value_kind:     by_value
      - .offset:         184
        .size:           4
        .value_kind:     hidden_block_count_x
      - .offset:         188
        .size:           4
        .value_kind:     hidden_block_count_y
      - .offset:         192
        .size:           4
        .value_kind:     hidden_block_count_z
      - .offset:         196
        .size:           2
        .value_kind:     hidden_group_size_x
      - .offset:         198
        .size:           2
        .value_kind:     hidden_group_size_y
      - .offset:         200
        .size:           2
        .value_kind:     hidden_group_size_z
      - .offset:         202
        .size:           2
        .value_kind:     hidden_remainder_x
      - .offset:         204
        .size:           2
        .value_kind:     hidden_remainder_y
      - .offset:         206
        .size:           2
        .value_kind:     hidden_remainder_z
      - .offset:         224
        .size:           8
        .value_kind:     hidden_global_offset_x
      - .offset:         232
        .size:           8
        .value_kind:     hidden_global_offset_y
      - .offset:         240
        .size:           8
        .value_kind:     hidden_global_offset_z
      - .offset:         248
        .size:           2
        .value_kind:     hidden_grid_dims
      - .offset:         272
        .size:           8
        .value_kind:     hidden_multigrid_sync_arg
      - .offset:         304
        .size:           4
        .value_kind:     hidden_dynamic_lds_size
    .group_segment_fixed_size: 0
    .kernarg_segment_align: 8
    .kernarg_segment_size: 440
    .language:       OpenCL C
    .language_version:
      - 2
      - 0
    .max_flat_workgroup_size: 512
    .name:           _Z14fwd_megakernel6Params
    .private_segment_fixed_size: 0
    .sgpr_count:     108
    .sgpr_spill_count: 423
    .symbol:         _Z14fwd_megakernel6Params.kd
    .uniform_work_group_size: 1
    .uses_dynamic_stack: false
    .vgpr_count:     256
    .vgpr_spill_count: 0
    .wavefront_size: 64
